# v45 plus: attention item prologue issues the second K/V tile loads together with the first (before the first barrier); wait ladder recounted
# speedup vs baseline: 1.0044x; 1.0044x over previous
; DI void attn_item(const Params& p, int seq, int hd, int qblk, char* smem, int tid_) {
;     ...
;   const size_t qrow = (size_t)seq * 2048 + qblk * 256 + w * 32 + r;
;   bf16x8 qf[12];
; #pragma unroll
;   for (int s = 0; s < 12; s++) qf[s] = *(const bf16x8*)(qb + qrow * 768 + hd * 192 + 16 * s + 8 * h);
;   f32x16 o[4];
; #pragma unroll
;   for (int db = 0; db < 4; db++)
; #pragma unroll
;     for (int i = 0; i < 16; i++) o[db][i] = 0.f;
;   float m = -1e30f, lsum = 0.f;
;   const u16* kg = kb + ((size_t)seq * 2048 + (tid >> 3)) * 768 + hd * 192 + (tid & 7) * 8;
;   const int kl = (tid >> 3) * 200 + (tid & 7) * 8;
;   const u16* vg = vt + ((size_t)(seq * 4 + hd) * 128 + (tid >> 3)) * 2048 + (tid & 7) * 8;
;   const int vl = (tid >> 3) * 72 + (tid & 7) * 8;
;   u32x4 rk[3], rv[2];
; #pragma unroll
;   for (int i = 0; i < 3; i++) rk[i] = *(const u32x4*)(kg + 64 * i);
; #pragma unroll
;   for (int i = 0; i < 2; i++) rv[i] = *(const u32x4*)(vg + (size_t)(64 * i) * 2048);
;   __syncthreads();
;   {
;     u16* sK0 = (u16*)smem;
;     u16* sV0 = sK0 + 64 * 200;
; #pragma unroll
;     for (int i = 0; i < 3; i++) *(u32x4*)(sK0 + kl + 64 * i) = rk[i];
; #pragma unroll
;     for (int i = 0; i < 2; i++) *(u32x4*)(sV0 + vl + 64 * i * 72) = rv[i];
;   }
;   __syncthreads();
; #pragma unroll
; DI void run_phase(const Params& p, int ph, char* smem, int* s_item, const XcdBarrier* xbp) {
;     ...
;       while (true) {
;         __syncthreads();
;         if (tid == 0) *s_item = atomicAdd(ctr, 1);
;         __syncthreads();
;         const int it = __builtin_amdgcn_readfirstlane(*s_item);
;         if (it >= 48 + 96 + 1536) break;
;         const int wv = __builtin_amdgcn_readfirstlane(tid >> 6);
;         const int half = wv >> 2, tl = tid & 255;
;         if (it < 48) {
;           gla_wave(p, l, it, wv >> 1, wv & 1, smem + wv * 13312, tid & 63);
;           __threadfence();
;           __syncthreads();
;           gla_combine(p, l, it, half, tl);
;         } else if (it < 144) {
;           const int a = it - 48;
;           lru_wave(p, l, a >> 1, 4 * (a & 1) + (wv >> 1), wv & 1, smem + wv * 13312, tid & 63);
;           __threadfence();
;           __syncthreads();
;           lru_combine(p, a >> 1, 2 * (a & 1) + half, tl);
;         } else {
;           const int a = it - 144;
;           attn_item(p, a >> 5, (a >> 3) & 3, a & 7, smem, tid);
.LBB0_620:
	s_or_b64 exec, exec, s[2:3]
	v_mov_b32_e32 v0, s45
	s_waitcnt lgkmcnt(0)
	s_barrier
	ds_read_b32 v0, v0
	s_mov_b64 s[2:3], -1
	s_waitcnt lgkmcnt(0)
	v_readfirstlane_b32 s42, v0
	s_cmpk_gt_i32 s42, 0x68f
	s_cbranch_scc1 .LBB0_615
	v_readfirstlane_b32 s23, v233
	s_ashr_i32 s26, s23, 6
	s_ashr_i32 s97, s23, 8
	s_cmp_gt_i32 s42, 47
	s_cbranch_scc0 .LBB0_647
	s_cmpk_gt_u32 s42, 0x8f
	s_cbranch_scc0 .LBB0_635
	s_add_i32 s1, s42, 0xffffff70
	s_lshr_b32 s5, s1, 5
	v_mov_b32_e32 v36, v233
	s_lshl_b32 s3, s42, 8
	s_lshl_b32 s2, s5, 11
	s_and_b32 s3, s3, 0x700
	v_ashrrev_i32_e32 v20, 3, v36
	s_or_b32 s88, s2, s3
	v_ashrrev_i32_e32 v0, 1, v36
	s_mov_b32 s3, s89
	v_ashrrev_i32_e32 v21, 31, v20
	v_and_b32_e32 v0, 0xffffffe0, v0
	v_lshl_add_u64 v[22:23], v[20:21], 0, s[2:3]
	v_readlane_b32 s2, v246, 25
	v_ashrrev_i32_e32 v1, 31, v0
	v_readlane_b32 s3, v246, 26
	s_movk_i32 s8, 0x600
	v_lshl_add_u64 v[180:181], v[0:1], 0, s[88:89]
	v_mov_b64_e32 v[0:1], s[2:3]
	s_bfe_u32 s1, s1, 0x20003
	v_mad_u64_u32 v[0:1], s[2:3], v22, s8, v[0:1]
	v_lshlrev_b32_e32 v2, 3, v36
	s_mul_i32 s88, s1, 0x180
	v_mad_i32_i24 v1, v23, s8, v1
	v_and_b32_e32 v24, 56, v2
	s_lshl_b32 s3, s5, 9
	s_lshl_b32 s2, s1, 7
	v_lshl_add_u64 v[0:1], v[0:1], 0, s[88:89]
	v_lshlrev_b32_e32 v8, 1, v24
	v_mov_b32_e32 v9, v189
	s_or_b32 s6, s2, s3
	s_mov_b32 s7, s89
	v_lshl_add_u64 v[26:27], v[0:1], 0, v[8:9]
	v_lshl_add_u64 v[0:1], v[20:21], 0, s[6:7]
	v_readlane_b32 s6, v246, 27
	v_lshlrev_b64 v[28:29], 12, v[0:1]
	v_readlane_b32 s7, v246, 28
	global_load_dwordx4 v[0:3], v[26:27], off
	global_load_dwordx4 v[4:7], v[26:27], off offset:128
	v_lshl_add_u64 v[10:11], s[6:7], 0, v[28:29]
	v_lshl_add_u64 v[30:31], v[10:11], 0, v[8:9]
	global_load_dwordx4 v[8:11], v[26:27], off offset:256
	global_load_dwordx4 v[12:15], v[30:31], off
	s_mov_b32 s1, 0x40000
	v_add_co_u32_e32 v32, vcc, s1, v30
	v_and_b32_e32 v37, 31, v36
	s_nop 0
	v_addc_co_u32_e32 v33, vcc, 0, v31, vcc
	global_load_dwordx4 v[16:19], v[32:33], off
	s_movk_i32 s1, 0xc8
	v_mov_b64_e32 v[34:35], s[84:85]
	v_lshlrev_b32_e32 v21, 7, v20
	v_mad_u64_u32 v[182:183], s[6:7], v20, s1, v[24:25]
	v_or_b32_e32 v180, v180, v37
	v_sub_u32_e32 v196, v182, v21
	v_mad_u64_u32 v[20:21], s[6:7], v180, s8, v[34:35]
	v_bfe_u32 v191, v36, 5, 1
	v_mad_i32_i24 v21, v181, s8, v21
	v_lshlrev_b32_e32 v188, 4, v191
	v_lshl_add_u64 v[20:21], v[20:21], 0, s[88:89]
	v_lshl_add_u64 v[20:21], v[20:21], 0, v[188:189]
	global_load_dwordx4 v[140:143], v[20:21], off
	global_load_dwordx4 v[136:139], v[20:21], off offset:32
	global_load_dwordx4 v[132:135], v[20:21], off offset:64
	global_load_dwordx4 v[128:131], v[20:21], off offset:96
	global_load_dwordx4 v[124:127], v[20:21], off offset:128
	global_load_dwordx4 v[120:123], v[20:21], off offset:160
	global_load_dwordx4 v[116:119], v[20:21], off offset:192
	global_load_dwordx4 v[112:115], v[20:21], off offset:224
	global_load_dwordx4 v[108:111], v[20:21], off offset:256
	global_load_dwordx4 v[104:107], v[20:21], off offset:288
	global_load_dwordx4 v[100:103], v[20:21], off offset:320
	global_load_dwordx4 v[96:99], v[20:21], off offset:352
	s_mov_b32 s1, 0x18000
	v_add_co_u32_e32 v24, vcc, s1, v26
	v_lshl_add_u32 v38, v182, 1, 0
	s_nop 0
	v_addc_co_u32_e32 v25, vcc, 0, v27, vcc
	v_lshl_add_u32 v39, v196, 1, 0
	global_load_dwordx4 v[144:147], v[24:25], off
	global_load_dwordx4 v[148:151], v[24:25], off offset:128
	global_load_dwordx4 v[152:155], v[24:25], off offset:256
	global_load_dwordx4 v[156:159], v[30:31], off offset:128
	global_load_dwordx4 v[160:163], v[32:33], off offset:128
	s_barrier
	v_readlane_b32 s6, v244, 25
	v_readlane_b32 s7, v244, 26
	v_mul_u32_u24_e32 v197, 0x190, v37
	v_mul_u32_u24_e32 v195, 0x90, v37
	s_mov_b32 s3, 0
	v_mov_b32_e32 v199, 0xf149f2ca
	v_mov_b32_e32 v194, 0
	s_waitcnt vmcnt(21)
	ds_write_b128 v38, v[0:3]
	s_waitcnt vmcnt(20)
	ds_write_b128 v38, v[4:7] offset:128
	s_waitcnt vmcnt(19)
	ds_write_b128 v38, v[8:11] offset:256
	s_waitcnt vmcnt(18)
	ds_write_b128 v39, v[12:15] offset:25600
	s_waitcnt vmcnt(17)
	ds_write_b128 v39, v[16:19] offset:34816
	s_waitcnt lgkmcnt(0)
	s_barrier
	v_mbcnt_hi_u32_b32 v0, -1, v224
	v_and_b32_e32 v2, 64, v0
	v_xor_b32_e32 v1, 32, v0
	v_add_u32_e32 v2, 64, v2
	v_cmp_lt_i32_e32 vcc, v1, v2
	v_mov_b32_e32 v14, v189
	v_mov_b32_e32 v15, v189
	v_cndmask_b32_e32 v0, v0, v1, vcc
	v_lshlrev_b32_e32 v183, 2, v0
	v_lshlrev_b32_e32 v0, 4, v36
	v_and_b32_e32 v2, 0x70, v0
	v_or_b32_e32 v28, v28, v2
	v_mov_b64_e32 v[0:1], s[88:89]
	v_lshl_add_u64 v[184:185], s[6:7], 0, v[28:29]
	v_mad_u64_u32 v[0:1], s[6:7], v22, s8, v[0:1]
	v_readlane_b32 s6, v244, 27
	v_mad_i32_i24 v1, v23, s8, v1
	v_or_b32_e32 v0, v0, v2
	v_readlane_b32 s7, v244, 28
	v_mov_b32_e32 v2, v189
	v_mov_b32_e32 v3, v189
	v_lshl_add_u64 v[186:187], s[6:7], 0, v[0:1]
	v_mov_b32_e32 v0, v189
	v_mov_b32_e32 v1, v189
	v_mov_b32_e32 v4, v189
	v_mov_b32_e32 v5, v189
	v_mov_b32_e32 v6, v189
	v_mov_b32_e32 v7, v189
	v_mov_b32_e32 v8, v189
	v_mov_b32_e32 v9, v189
	v_mov_b32_e32 v10, v189
	v_mov_b32_e32 v11, v189
	v_mov_b32_e32 v12, v189
	v_mov_b32_e32 v13, v189
	v_mov_b64_e32 v[30:31], v[14:15]
	v_mov_b64_e32 v[46:47], v[14:15]
	v_mov_b64_e32 v[62:63], v[14:15]
	v_mov_b64_e32 v[28:29], v[12:13]
	v_mov_b64_e32 v[26:27], v[10:11]
	v_mov_b64_e32 v[24:25], v[8:9]
	v_mov_b64_e32 v[22:23], v[6:7]
	v_mov_b64_e32 v[20:21], v[4:5]
	v_mov_b64_e32 v[18:19], v[2:3]
	v_mov_b64_e32 v[16:17], v[0:1]
	v_mov_b64_e32 v[44:45], v[12:13]
	v_mov_b64_e32 v[42:43], v[10:11]
	v_mov_b64_e32 v[40:41], v[8:9]
	v_mov_b64_e32 v[38:39], v[6:7]
	v_mov_b64_e32 v[36:37], v[4:5]
	v_mov_b64_e32 v[34:35], v[2:3]
	v_mov_b64_e32 v[32:33], v[0:1]
	v_mov_b64_e32 v[60:61], v[12:13]
	v_mov_b64_e32 v[58:59], v[10:11]
	v_mov_b64_e32 v[56:57], v[8:9]
	v_mov_b64_e32 v[54:55], v[6:7]
	v_mov_b64_e32 v[52:53], v[4:5]
	v_mov_b64_e32 v[50:51], v[2:3]
	v_mov_b64_e32 v[48:49], v[0:1]
